# SSD prompt unit output stage: the LDS reads of all four rows issued at the top of the stage (counted lgkmcnt), on top of v59
# speedup vs baseline: 1.0099x; 1.0048x over previous
.LBB0_368:
	v_add_u32_e32 v218, v128, v132
	ds_read_b128 v[74:77], v218
	ds_read_b128 v[220:223], v203
	ds_read_b128 v[78:81], v218 offset:64
	ds_read_b128 v[224:227], v203 offset:64
	ds_read_b128 v[228:231], v218 offset:128
	ds_read_b128 v[232:235], v203 offset:128
	ds_read_b128 v[236:239], v218 offset:192
	s_waitcnt lgkmcnt(6)
	v_mfma_f32_16x16x32_bf16 v[74:77], v[66:69], v[74:77], 0
	s_waitcnt lgkmcnt(5)
	v_mfma_f32_16x16x32_bf16 v[220:223], v[66:69], v[220:223], 0
	ds_read_b128 v[66:69], v203 offset:192
	s_waitcnt lgkmcnt(5)
	v_mfma_f32_16x16x32_bf16 v[74:77], v[62:65], v[78:81], v[74:77]
	s_waitcnt lgkmcnt(4)
	v_mfma_f32_16x16x32_bf16 v[220:223], v[62:65], v[224:227], v[220:223]
	s_waitcnt lgkmcnt(3)
	v_mfma_f32_16x16x32_bf16 v[74:77], v[58:61], v[228:231], v[74:77]
	s_waitcnt lgkmcnt(2)
	v_mfma_f32_16x16x32_bf16 v[220:223], v[58:61], v[232:235], v[220:223]
	s_waitcnt lgkmcnt(1)
	v_mfma_f32_16x16x32_bf16 v[74:77], v[70:73], v[236:239], v[74:77]
	s_waitcnt lgkmcnt(0)
	v_mfma_f32_16x16x32_bf16 v[58:61], v[70:73], v[66:69], v[220:223]
	s_waitcnt vmcnt(9)
	s_nop 7
	ds_read_b32 v62, v166
	ds_read_u16 v68, v167
	ds_read_u16 v73, v167 offset:32
	ds_read_b32 v220, v168
	ds_read_u16 v221, v169
	ds_read_u16 v222, v169 offset:32
	ds_read_b32 v223, v170
	ds_read_u16 v224, v171
	ds_read_u16 v225, v171 offset:32
	ds_read_b32 v226, v173
	ds_read_u16 v227, v175
	ds_read_u16 v228, v175 offset:32
	s_waitcnt lgkmcnt(11)
	v_mul_f32_e32 v62, 0x3fb8aa3b, v62
	v_exp_f32_e32 v72, v62
	s_waitcnt lgkmcnt(10)
	v_lshlrev_b32_e32 v68, 16, v68
	v_add_u32_e32 v62, -3, v118
	v_ashrrev_i32_e32 v63, 31, v62
	v_fma_f32 v54, v74, v72, v54
	v_fmac_f32_e32 v54, v208, v68
	v_lshlrev_b32_e32 v68, 16, v217
	v_mul_f32_e32 v69, 0xbfb8aa3b, v68
	v_exp_f32_e32 v69, v69
	v_fma_f32 v50, v58, v72, v50
	v_lshlrev_b32_e32 v58, 16, v216
	v_add_f32_e32 v69, 1.0, v69
	v_rcp_f32_e32 v69, v69
	s_nop 0
	v_mul_f32_e32 v68, v69, v68
	v_mul_f32_e32 v54, v68, v54
	v_lshlrev_b64 v[68:69], 12, v[62:63]
	v_lshl_or_b32 v68, s94, 1, v68
	v_cvt_pk_bf16_f32 v74, v54, s0
	v_lshl_add_u64 v[70:71], v[98:99], 0, v[68:69]
	global_store_short v[70:71], v74, off
	s_waitcnt lgkmcnt(9)
	v_lshlrev_b32_e32 v70, 16, v73
	v_fmac_f32_e32 v50, v208, v70
	v_mul_f32_e32 v70, 0xbfb8aa3b, v58
	v_exp_f32_e32 v70, v70
	v_lshl_add_u64 v[68:69], v[116:117], 0, v[68:69]
	v_add_f32_e32 v70, 1.0, v70
	v_rcp_f32_e32 v70, v70
	s_nop 0
	v_mul_f32_e32 v58, v70, v58
	v_mul_f32_e32 v50, v58, v50
	v_mul_f32_e32 v58, v50, v50
	v_fmac_f32_e32 v58, v54, v54
	v_cvt_pk_bf16_f32 v50, v50, s0
	global_store_short v[68:69], v50, off
	s_waitcnt lgkmcnt(0)
	s_nop 1
	v_add_f32_dpp v50, v58, v58 quad_perm:[1,0,3,2] row_mask:0xf bank_mask:0xf
	s_waitcnt lgkmcnt(0)
	s_nop 1
	v_add_f32_dpp v50, v50, v50 quad_perm:[2,3,0,1] row_mask:0xf bank_mask:0xf
	s_waitcnt lgkmcnt(0)
	s_nop 1
	v_add_f32_dpp v50, v50, v50 row_half_mirror row_mask:0xf bank_mask:0xf
	s_nop 1
	v_add_f32_dpp v54, v50, v50 row_mirror row_mask:0xf bank_mask:0xf
	s_and_saveexec_b64 s[24:25], s[4:5]
	s_cbranch_execz .LBB0_370
	v_lshlrev_b64 v[62:63], 8, v[62:63]
	s_waitcnt lgkmcnt(0)
	v_mov_b32_e32 v50, v54
	v_lshl_add_u64 v[62:63], s[88:89], 0, v[62:63]
	global_store_dword v[62:63], v50, off
.LBB0_370:
	s_or_b64 exec, exec, s[24:25]
	v_lshlrev_b32_e32 v62, 16, v215
	v_mul_f32_e32 v63, 0xbfb8aa3b, v62
	v_mov_b32_e32 v50, v220
	s_waitcnt lgkmcnt(1)
	v_mov_b32_e32 v54, v221
	v_mov_b32_e32 v58, v222
	v_exp_f32_e32 v63, v63
	v_lshlrev_b32_e32 v68, 16, v214
	s_waitcnt lgkmcnt(2)
	v_mul_f32_e32 v50, 0x3fb8aa3b, v50
	v_exp_f32_e32 v50, v50
	v_add_f32_e32 v63, 1.0, v63
	v_rcp_f32_e32 v63, v63
	v_mul_f32_e32 v69, 0xbfb8aa3b, v68
	v_exp_f32_e32 v69, v69
	s_waitcnt lgkmcnt(1)
	v_lshlrev_b32_e32 v54, 16, v54
	v_fma_f32 v55, v75, v50, v55
	v_fmac_f32_e32 v55, v208, v54
	v_mul_f32_e32 v54, v63, v62
	v_mul_f32_e32 v54, v54, v55
	v_add_f32_e32 v55, 1.0, v69
	v_rcp_f32_e32 v55, v55
	s_waitcnt lgkmcnt(0)
	v_lshlrev_b32_e32 v58, 16, v58
	v_fma_f32 v50, v59, v50, v51
	v_fmac_f32_e32 v50, v208, v58
	v_mul_f32_e32 v51, v55, v68
	v_mul_f32_e32 v68, v51, v50
	v_mul_f32_e32 v50, v68, v68
	v_fmac_f32_e32 v50, v54, v54
	v_cvt_pk_bf16_f32 v70, v54, s0
	s_waitcnt lgkmcnt(0)
	s_nop 1
	v_add_f32_dpp v55, v50, v50 quad_perm:[1,0,3,2] row_mask:0xf bank_mask:0xf
	v_add_u32_e32 v50, -2, v118
	v_ashrrev_i32_e32 v51, 31, v50
	s_waitcnt lgkmcnt(0)
	s_nop 1
	v_add_f32_dpp v55, v55, v55 quad_perm:[2,3,0,1] row_mask:0xf bank_mask:0xf
	v_lshlrev_b64 v[58:59], 12, v[50:51]
	v_lshl_or_b32 v58, s94, 1, v58
	v_lshl_add_u64 v[62:63], v[98:99], 0, v[58:59]
	global_store_short v[62:63], v70, off
	s_waitcnt lgkmcnt(0)
	s_nop 1
	v_add_f32_dpp v54, v55, v55 row_half_mirror row_mask:0xf bank_mask:0xf
	s_nop 1
	v_add_f32_dpp v55, v54, v54 row_mirror row_mask:0xf bank_mask:0xf
	v_cvt_pk_bf16_f32 v62, v68, s0
	v_lshl_add_u64 v[58:59], v[116:117], 0, v[58:59]
	global_store_short v[58:59], v62, off
	s_and_saveexec_b64 s[24:25], s[4:5]
	s_cbranch_execz .LBB0_372
	v_lshlrev_b64 v[50:51], 8, v[50:51]
	s_waitcnt lgkmcnt(0)
	v_mov_b32_e32 v54, v55
	v_lshl_add_u64 v[50:51], s[88:89], 0, v[50:51]
	global_store_dword v[50:51], v54, off
.LBB0_372:
	s_or_b64 exec, exec, s[24:25]
	s_waitcnt lgkmcnt(0)
	v_lshlrev_b32_e32 v55, 16, v213
	v_mul_f32_e32 v58, 0xbfb8aa3b, v55
	v_mov_b32_e32 v50, v223
	v_mov_b32_e32 v51, v224
	v_mov_b32_e32 v54, v225
	v_exp_f32_e32 v58, v58
	v_lshlrev_b32_e32 v59, 16, v212
	s_waitcnt lgkmcnt(2)
	v_mul_f32_e32 v50, 0x3fb8aa3b, v50
	v_exp_f32_e32 v50, v50
	v_add_f32_e32 v58, 1.0, v58
	v_rcp_f32_e32 v58, v58
	v_mul_f32_e32 v62, 0xbfb8aa3b, v59
	v_exp_f32_e32 v62, v62
	s_waitcnt lgkmcnt(1)
	v_lshlrev_b32_e32 v51, 16, v51
	v_fma_f32 v56, v76, v50, v56
	v_fmac_f32_e32 v56, v208, v51
	v_mul_f32_e32 v51, v58, v55
	v_mul_f32_e32 v55, v51, v56
	v_add_f32_e32 v51, 1.0, v62
	v_rcp_f32_e32 v51, v51
	s_waitcnt lgkmcnt(0)
	v_lshlrev_b32_e32 v54, 16, v54
	v_fma_f32 v50, v60, v50, v52
	v_fmac_f32_e32 v50, v208, v54
	v_mul_f32_e32 v51, v51, v59
	v_mul_f32_e32 v56, v51, v50
	v_mul_f32_e32 v50, v56, v56
	v_fmac_f32_e32 v50, v55, v55
	v_cvt_pk_bf16_f32 v55, v55, s0
	s_waitcnt lgkmcnt(0)
	s_nop 1
	v_add_f32_dpp v52, v50, v50 quad_perm:[1,0,3,2] row_mask:0xf bank_mask:0xf
	v_add_u32_e32 v50, -1, v118
	v_ashrrev_i32_e32 v51, 31, v50
	v_lshlrev_b64 v[58:59], 12, v[50:51]
	v_lshl_or_b32 v58, s94, 1, v58
	s_waitcnt lgkmcnt(0)
	s_nop 1
	v_add_f32_dpp v52, v52, v52 quad_perm:[2,3,0,1] row_mask:0xf bank_mask:0xf
	v_lshl_add_u64 v[62:63], v[98:99], 0, v[58:59]
	global_store_short v[62:63], v55, off
	v_cvt_pk_bf16_f32 v55, v56, s0
	v_lshl_add_u64 v[58:59], v[116:117], 0, v[58:59]
	s_waitcnt lgkmcnt(0)
	s_nop 1
	v_add_f32_dpp v52, v52, v52 row_half_mirror row_mask:0xf bank_mask:0xf
	s_nop 1
	v_add_f32_dpp v54, v52, v52 row_mirror row_mask:0xf bank_mask:0xf
	global_store_short v[58:59], v55, off
	s_and_saveexec_b64 s[24:25], s[4:5]
	s_cbranch_execz .LBB0_374
	v_lshlrev_b64 v[50:51], 8, v[50:51]
	s_waitcnt lgkmcnt(0)
	v_mov_b32_e32 v52, v54
	v_lshl_add_u64 v[50:51], s[88:89], 0, v[50:51]
	global_store_dword v[50:51], v52, off
.LBB0_374:
	s_or_b64 exec, exec, s[24:25]
	s_waitcnt lgkmcnt(0)
	v_lshlrev_b32_e32 v54, 16, v119
	v_mul_f32_e32 v55, 0xbfb8aa3b, v54
	v_mov_b32_e32 v50, v226
	v_mov_b32_e32 v51, v227
	v_mov_b32_e32 v52, v228
	v_exp_f32_e32 v55, v55
	v_lshlrev_b32_e32 v56, 16, v97
	s_waitcnt lgkmcnt(2)
	v_mul_f32_e32 v50, 0x3fb8aa3b, v50
	v_exp_f32_e32 v50, v50
	v_add_f32_e32 v55, 1.0, v55
	v_mul_f32_e32 v58, 0xbfb8aa3b, v56
	v_rcp_f32_e32 v55, v55
	v_exp_f32_e32 v58, v58
	s_waitcnt lgkmcnt(1)
	v_lshlrev_b32_e32 v51, 16, v51
	v_fmac_f32_e32 v57, v77, v50
	v_fmac_f32_e32 v57, v208, v51
	v_mul_f32_e32 v51, v55, v54
	v_add_f32_e32 v54, 1.0, v58
	v_rcp_f32_e32 v54, v54
	s_waitcnt lgkmcnt(0)
	v_lshlrev_b32_e32 v52, 16, v52
	v_fmac_f32_e32 v53, v61, v50
	v_fmac_f32_e32 v53, v208, v52
	v_mul_f32_e32 v50, v54, v56
	v_mul_f32_e32 v56, v50, v53
	v_mul_f32_e32 v51, v51, v57
	v_mul_f32_e32 v50, v56, v56
	v_fmac_f32_e32 v50, v51, v51
	v_ashrrev_i32_e32 v119, 31, v118
	v_cvt_pk_bf16_f32 v58, v51, s0
	s_waitcnt lgkmcnt(0)
	s_nop 1
	v_add_f32_dpp v50, v50, v50 quad_perm:[1,0,3,2] row_mask:0xf bank_mask:0xf
	s_waitcnt lgkmcnt(0)
	s_nop 1
	v_add_f32_dpp v50, v50, v50 quad_perm:[2,3,0,1] row_mask:0xf bank_mask:0xf
	v_lshlrev_b64 v[52:53], 12, v[118:119]
	v_lshl_or_b32 v52, s94, 1, v52
	v_lshl_add_u64 v[54:55], v[98:99], 0, v[52:53]
	global_store_short v[54:55], v58, off
	s_waitcnt lgkmcnt(0)
	s_nop 1
	v_add_f32_dpp v50, v50, v50 row_half_mirror row_mask:0xf bank_mask:0xf
	s_nop 1
	v_add_f32_dpp v51, v50, v50 row_mirror row_mask:0xf bank_mask:0xf
	v_cvt_pk_bf16_f32 v54, v56, s0
	v_lshl_add_u64 v[52:53], v[116:117], 0, v[52:53]
	global_store_short v[52:53], v54, off
	s_and_saveexec_b64 s[24:25], s[4:5]
	s_cbranch_execz .LBB0_376
	s_waitcnt lgkmcnt(0)
	v_mov_b32_e32 v52, v51
	v_lshlrev_b64 v[50:51], 8, v[118:119]
	v_lshl_add_u64 v[50:51], s[88:89], 0, v[50:51]
	global_store_dword v[50:51], v52, off
